# P9 sample-row tiles: hid stores write-through (sc1) and publish without the L2 write-back fence (704 buffer_wbl2 removed from the critical 12-unit workgroups)
# speedup vs baseline: 1.0214x; 1.0196x over previous
.LBB0_1243:
	ds_read_b128 v[170:173], v162
	ds_read_b128 v[174:177], v162 offset:1024
	ds_read_b128 v[178:181], v162 offset:2048
	ds_read_b128 v[182:185], v162 offset:3072
	s_add_u32 s34, s30, 0xfffc0080
	s_addc_u32 s35, s31, -1
	s_cmp_eq_u32 s41, 12
	s_cselect_b32 s37, s11, s35
	s_cselect_b32 s36, s17, s34
	s_cselect_b32 s35, s29, s40
	s_cselect_b32 s34, s38, s39
	v_lshl_add_u64 v[144:145], s[30:31], 0, v[134:135]
	s_add_i32 m0, s48, 0xc000
	ds_read_b128 v[186:189], v163
	ds_read_b128 v[190:193], v163 offset:1024
	ds_read_b128 v[194:197], v163 offset:2048
	ds_read_b128 v[198:201], v163 offset:3072
	ds_read_b128 v[204:207], v163 offset:4096
	ds_read_b128 v[208:211], v163 offset:5120
	ds_read_b128 v[212:215], v163 offset:6144
	ds_read_b128 v[216:219], v163 offset:7168
	global_load_lds_dwordx4 v[144:145], off
	v_lshl_add_u64 v[144:145], s[30:31], 0, v[136:137]
	s_add_i32 m0, s48, 0xe000
	s_nop 0
	global_load_lds_dwordx4 v[144:145], off
	ds_read_b128 v[220:223], v164
	ds_read_b128 v[224:227], v164 offset:1024
	ds_read_b128 v[228:231], v164 offset:2048
	ds_read_b128 v[232:235], v164 offset:3072
	s_waitcnt lgkmcnt(0)
	s_waitcnt vmcnt(8)
	s_barrier
	s_setprio 1
	v_mfma_f32_16x16x32_bf16 v[124:127], v[170:173], v[186:189], v[124:127]
	v_mfma_f32_16x16x32_bf16 v[120:123], v[178:181], v[186:189], v[120:123]
	v_mfma_f32_16x16x32_bf16 v[112:115], v[170:173], v[194:197], v[112:115]
	v_mfma_f32_16x16x32_bf16 v[104:107], v[178:181], v[194:197], v[104:107]
	v_mfma_f32_16x16x32_bf16 v[96:99], v[170:173], v[204:207], v[96:99]
	v_mfma_f32_16x16x32_bf16 v[88:91], v[178:181], v[204:207], v[88:91]
	v_mfma_f32_16x16x32_bf16 v[80:83], v[170:173], v[212:215], v[80:83]
	v_mfma_f32_16x16x32_bf16 v[72:75], v[178:181], v[212:215], v[72:75]
	v_mfma_f32_16x16x32_bf16 v[124:127], v[174:177], v[190:193], v[124:127]
	v_mfma_f32_16x16x32_bf16 v[120:123], v[182:185], v[190:193], v[120:123]
	v_mfma_f32_16x16x32_bf16 v[112:115], v[174:177], v[198:201], v[112:115]
	v_mfma_f32_16x16x32_bf16 v[104:107], v[182:185], v[198:201], v[104:107]
	v_mfma_f32_16x16x32_bf16 v[96:99], v[174:177], v[208:211], v[96:99]
	v_mfma_f32_16x16x32_bf16 v[88:91], v[182:185], v[208:211], v[88:91]
	v_mfma_f32_16x16x32_bf16 v[80:83], v[174:177], v[216:219], v[80:83]
	v_mfma_f32_16x16x32_bf16 v[72:75], v[182:185], v[216:219], v[72:75]
	v_mfma_f32_16x16x32_bf16 v[116:119], v[220:223], v[186:189], v[116:119]
	v_mfma_f32_16x16x32_bf16 v[108:111], v[228:231], v[186:189], v[108:111]
	v_mfma_f32_16x16x32_bf16 v[100:103], v[220:223], v[194:197], v[100:103]
	v_mfma_f32_16x16x32_bf16 v[92:95], v[228:231], v[194:197], v[92:95]
	v_mfma_f32_16x16x32_bf16 v[84:87], v[220:223], v[204:207], v[84:87]
	v_mfma_f32_16x16x32_bf16 v[76:79], v[228:231], v[204:207], v[76:79]
	v_mfma_f32_16x16x32_bf16 v[68:71], v[220:223], v[212:215], v[68:71]
	v_mfma_f32_16x16x32_bf16 v[64:67], v[228:231], v[212:215], v[64:67]
	v_mfma_f32_16x16x32_bf16 v[116:119], v[224:227], v[190:193], v[116:119]
	v_mfma_f32_16x16x32_bf16 v[108:111], v[232:235], v[190:193], v[108:111]
	v_mfma_f32_16x16x32_bf16 v[100:103], v[224:227], v[198:201], v[100:103]
	v_mfma_f32_16x16x32_bf16 v[92:95], v[232:235], v[198:201], v[92:95]
	v_mfma_f32_16x16x32_bf16 v[84:87], v[224:227], v[208:211], v[84:87]
	v_mfma_f32_16x16x32_bf16 v[76:79], v[232:235], v[208:211], v[76:79]
	v_mfma_f32_16x16x32_bf16 v[68:71], v[224:227], v[216:219], v[68:71]
	v_mfma_f32_16x16x32_bf16 v[64:67], v[232:235], v[216:219], v[64:67]
	s_setprio 0
	s_barrier
	ds_read_b128 v[186:189], v163 offset:16384
	ds_read_b128 v[190:193], v163 offset:17408
	ds_read_b128 v[194:197], v163 offset:18432
	ds_read_b128 v[198:201], v163 offset:19456
	ds_read_b128 v[204:207], v163 offset:20480
	ds_read_b128 v[208:211], v163 offset:21504
	ds_read_b128 v[212:215], v163 offset:22528
	ds_read_b128 v[216:219], v163 offset:23552
	s_mov_b32 m0, s46
	v_lshl_add_u64 v[144:145], s[34:35], 0, v[128:129]
	global_load_lds_dwordx4 v[144:145], off
	v_lshl_add_u64 v[236:237], s[34:35], 0, v[130:131]
	s_mov_b32 m0, s47
	s_nop 0
	global_load_lds_dwordx4 v[236:237], off
	s_mov_b32 m0, s48
	v_lshl_add_u64 v[238:239], s[36:37], 0, v[128:129]
	global_load_lds_dwordx4 v[238:239], off
	v_lshl_add_u64 v[240:241], s[36:37], 0, v[130:131]
	s_mov_b32 m0, s49
	s_nop 0
	global_load_lds_dwordx4 v[240:241], off
	s_add_u32 s72, s34, 0x40000
	s_addc_u32 s73, s35, 0
	s_mov_b32 m0, s50
	v_lshl_add_u64 v[248:249], s[72:73], 0, v[128:129]
	global_load_lds_dwordx4 v[248:249], off
	v_lshl_add_u64 v[248:249], s[72:73], 0, v[130:131]
	s_mov_b32 m0, s51
	s_nop 0
	global_load_lds_dwordx4 v[248:249], off
	s_waitcnt lgkmcnt(0)
	s_waitcnt vmcnt(8)
	s_barrier
	s_setprio 1
	v_mfma_f32_16x16x32_bf16 v[60:63], v[170:173], v[186:189], v[60:63]
	v_mfma_f32_16x16x32_bf16 v[56:59], v[178:181], v[186:189], v[56:59]
	v_mfma_f32_16x16x32_bf16 v[48:51], v[170:173], v[194:197], v[48:51]
	v_mfma_f32_16x16x32_bf16 v[40:43], v[178:181], v[194:197], v[40:43]
	v_mfma_f32_16x16x32_bf16 v[32:35], v[170:173], v[204:207], v[32:35]
	v_mfma_f32_16x16x32_bf16 v[24:27], v[178:181], v[204:207], v[24:27]
	v_mfma_f32_16x16x32_bf16 v[16:19], v[170:173], v[212:215], v[16:19]
	v_mfma_f32_16x16x32_bf16 v[8:11], v[178:181], v[212:215], v[8:11]
	v_mfma_f32_16x16x32_bf16 v[60:63], v[174:177], v[190:193], v[60:63]
	v_mfma_f32_16x16x32_bf16 v[56:59], v[182:185], v[190:193], v[56:59]
	v_mfma_f32_16x16x32_bf16 v[48:51], v[174:177], v[198:201], v[48:51]
	v_mfma_f32_16x16x32_bf16 v[40:43], v[182:185], v[198:201], v[40:43]
	v_mfma_f32_16x16x32_bf16 v[32:35], v[174:177], v[208:211], v[32:35]
	v_mfma_f32_16x16x32_bf16 v[24:27], v[182:185], v[208:211], v[24:27]
	v_mfma_f32_16x16x32_bf16 v[16:19], v[174:177], v[216:219], v[16:19]
	v_mfma_f32_16x16x32_bf16 v[8:11], v[182:185], v[216:219], v[8:11]
	v_mfma_f32_16x16x32_bf16 v[52:55], v[220:223], v[186:189], v[52:55]
	v_mfma_f32_16x16x32_bf16 v[44:47], v[228:231], v[186:189], v[44:47]
	v_mfma_f32_16x16x32_bf16 v[36:39], v[220:223], v[194:197], v[36:39]
	v_mfma_f32_16x16x32_bf16 v[28:31], v[228:231], v[194:197], v[28:31]
	v_mfma_f32_16x16x32_bf16 v[20:23], v[220:223], v[204:207], v[20:23]
	v_mfma_f32_16x16x32_bf16 v[12:15], v[228:231], v[204:207], v[12:15]
	v_mfma_f32_16x16x32_bf16 v[4:7], v[220:223], v[212:215], v[4:7]
	v_mfma_f32_16x16x32_bf16 v[0:3], v[228:231], v[212:215], v[0:3]
	v_mfma_f32_16x16x32_bf16 v[52:55], v[224:227], v[190:193], v[52:55]
	v_mfma_f32_16x16x32_bf16 v[44:47], v[232:235], v[190:193], v[44:47]
	v_mfma_f32_16x16x32_bf16 v[36:39], v[224:227], v[198:201], v[36:39]
	v_mfma_f32_16x16x32_bf16 v[28:31], v[232:235], v[198:201], v[28:31]
	v_mfma_f32_16x16x32_bf16 v[20:23], v[224:227], v[208:211], v[20:23]
	v_mfma_f32_16x16x32_bf16 v[12:15], v[232:235], v[208:211], v[12:15]
	v_mfma_f32_16x16x32_bf16 v[4:7], v[224:227], v[216:219], v[4:7]
	v_mfma_f32_16x16x32_bf16 v[0:3], v[232:235], v[216:219], v[0:3]
	s_setprio 0
	s_barrier
	ds_read_b128 v[170:173], v165
	ds_read_b128 v[174:177], v165 offset:1024
	ds_read_b128 v[178:181], v165 offset:2048
	ds_read_b128 v[182:185], v165 offset:3072
	s_add_u32 s36, s36, 0x40000
	s_addc_u32 s37, s37, 0
	s_mov_b32 m0, s52
	v_lshl_add_u64 v[220:221], s[36:37], 0, v[128:129]
	ds_read_b128 v[186:189], v163 offset:32768
	ds_read_b128 v[190:193], v163 offset:33792
	ds_read_b128 v[194:197], v163 offset:34816
	ds_read_b128 v[198:201], v163 offset:35840
	ds_read_b128 v[204:207], v163 offset:36864
	ds_read_b128 v[208:211], v163 offset:37888
	ds_read_b128 v[212:215], v163 offset:38912
	ds_read_b128 v[216:219], v163 offset:39936
	global_load_lds_dwordx4 v[220:221], off
	v_lshl_add_u64 v[220:221], s[36:37], 0, v[130:131]
	s_mov_b32 m0, s53
	s_nop 0
	global_load_lds_dwordx4 v[220:221], off
	ds_read_b128 v[220:223], v166
	ds_read_b128 v[224:227], v166 offset:1024
	ds_read_b128 v[228:231], v166 offset:2048
	ds_read_b128 v[232:235], v166 offset:3072
	s_waitcnt lgkmcnt(0)
	s_waitcnt vmcnt(8)
	s_barrier
	s_setprio 1
	v_mfma_f32_16x16x32_bf16 v[124:127], v[170:173], v[186:189], v[124:127]
	v_mfma_f32_16x16x32_bf16 v[120:123], v[178:181], v[186:189], v[120:123]
	v_mfma_f32_16x16x32_bf16 v[112:115], v[170:173], v[194:197], v[112:115]
	v_mfma_f32_16x16x32_bf16 v[104:107], v[178:181], v[194:197], v[104:107]
	v_mfma_f32_16x16x32_bf16 v[96:99], v[170:173], v[204:207], v[96:99]
	v_mfma_f32_16x16x32_bf16 v[88:91], v[178:181], v[204:207], v[88:91]
	v_mfma_f32_16x16x32_bf16 v[80:83], v[170:173], v[212:215], v[80:83]
	v_mfma_f32_16x16x32_bf16 v[72:75], v[178:181], v[212:215], v[72:75]
	v_mfma_f32_16x16x32_bf16 v[124:127], v[174:177], v[190:193], v[124:127]
	v_mfma_f32_16x16x32_bf16 v[120:123], v[182:185], v[190:193], v[120:123]
	v_mfma_f32_16x16x32_bf16 v[112:115], v[174:177], v[198:201], v[112:115]
	v_mfma_f32_16x16x32_bf16 v[104:107], v[182:185], v[198:201], v[104:107]
	v_mfma_f32_16x16x32_bf16 v[96:99], v[174:177], v[208:211], v[96:99]
	v_mfma_f32_16x16x32_bf16 v[88:91], v[182:185], v[208:211], v[88:91]
	v_mfma_f32_16x16x32_bf16 v[80:83], v[174:177], v[216:219], v[80:83]
	v_mfma_f32_16x16x32_bf16 v[72:75], v[182:185], v[216:219], v[72:75]
	v_mfma_f32_16x16x32_bf16 v[116:119], v[220:223], v[186:189], v[116:119]
	v_mfma_f32_16x16x32_bf16 v[108:111], v[228:231], v[186:189], v[108:111]
	v_mfma_f32_16x16x32_bf16 v[100:103], v[220:223], v[194:197], v[100:103]
	v_mfma_f32_16x16x32_bf16 v[92:95], v[228:231], v[194:197], v[92:95]
	v_mfma_f32_16x16x32_bf16 v[84:87], v[220:223], v[204:207], v[84:87]
	v_mfma_f32_16x16x32_bf16 v[76:79], v[228:231], v[204:207], v[76:79]
	v_mfma_f32_16x16x32_bf16 v[68:71], v[220:223], v[212:215], v[68:71]
	v_mfma_f32_16x16x32_bf16 v[64:67], v[228:231], v[212:215], v[64:67]
	v_mfma_f32_16x16x32_bf16 v[116:119], v[224:227], v[190:193], v[116:119]
	v_mfma_f32_16x16x32_bf16 v[108:111], v[232:235], v[190:193], v[108:111]
	v_mfma_f32_16x16x32_bf16 v[100:103], v[224:227], v[198:201], v[100:103]
	v_mfma_f32_16x16x32_bf16 v[92:95], v[232:235], v[198:201], v[92:95]
	v_mfma_f32_16x16x32_bf16 v[84:87], v[224:227], v[208:211], v[84:87]
	v_mfma_f32_16x16x32_bf16 v[76:79], v[232:235], v[208:211], v[76:79]
	v_mfma_f32_16x16x32_bf16 v[68:71], v[224:227], v[216:219], v[68:71]
	v_mfma_f32_16x16x32_bf16 v[64:67], v[232:235], v[216:219], v[64:67]
	s_setprio 0
	s_barrier
	ds_read_b128 v[186:189], v163 offset:49152
	ds_read_b128 v[190:193], v163 offset:50176
	ds_read_b128 v[194:197], v163 offset:51200
	ds_read_b128 v[198:201], v163 offset:52224
	ds_read_b128 v[204:207], v163 offset:53248
	ds_read_b128 v[208:211], v163 offset:54272
	ds_read_b128 v[212:215], v163 offset:55296
	ds_read_b128 v[216:219], v163 offset:56320
	s_mov_b32 m0, s54
	v_lshl_add_u64 v[144:145], v[144:145], 0, s[12:13]
	global_load_lds_dwordx4 v[144:145], off
	v_lshl_add_u64 v[144:145], v[236:237], 0, s[12:13]
	s_mov_b32 m0, s55
	s_nop 0
	global_load_lds_dwordx4 v[144:145], off
	s_mov_b32 m0, s56
	v_lshl_add_u64 v[144:145], v[238:239], 0, s[12:13]
	global_load_lds_dwordx4 v[144:145], off
	v_lshl_add_u64 v[144:145], v[240:241], 0, s[12:13]
	s_mov_b32 m0, s57
	s_nop 0
	global_load_lds_dwordx4 v[144:145], off
	s_add_u32 s34, s34, 0x40080
	s_addc_u32 s35, s35, 0
	s_mov_b32 m0, s58
	v_lshl_add_u64 v[144:145], s[34:35], 0, v[128:129]
	global_load_lds_dwordx4 v[144:145], off
	v_lshl_add_u64 v[144:145], s[34:35], 0, v[130:131]
	s_mov_b32 m0, s59
	s_nop 0
	global_load_lds_dwordx4 v[144:145], off
	s_waitcnt lgkmcnt(0)
	s_waitcnt vmcnt(8)
	s_barrier
	s_setprio 1
	v_mfma_f32_16x16x32_bf16 v[60:63], v[170:173], v[186:189], v[60:63]
	v_mfma_f32_16x16x32_bf16 v[56:59], v[178:181], v[186:189], v[56:59]
	v_mfma_f32_16x16x32_bf16 v[48:51], v[170:173], v[194:197], v[48:51]
	v_mfma_f32_16x16x32_bf16 v[40:43], v[178:181], v[194:197], v[40:43]
	v_mfma_f32_16x16x32_bf16 v[32:35], v[170:173], v[204:207], v[32:35]
	v_mfma_f32_16x16x32_bf16 v[24:27], v[178:181], v[204:207], v[24:27]
	v_mfma_f32_16x16x32_bf16 v[16:19], v[170:173], v[212:215], v[16:19]
	v_mfma_f32_16x16x32_bf16 v[8:11], v[178:181], v[212:215], v[8:11]
	v_mfma_f32_16x16x32_bf16 v[60:63], v[174:177], v[190:193], v[60:63]
	v_mfma_f32_16x16x32_bf16 v[56:59], v[182:185], v[190:193], v[56:59]
	v_mfma_f32_16x16x32_bf16 v[48:51], v[174:177], v[198:201], v[48:51]
	v_mfma_f32_16x16x32_bf16 v[40:43], v[182:185], v[198:201], v[40:43]
	v_mfma_f32_16x16x32_bf16 v[32:35], v[174:177], v[208:211], v[32:35]
	v_mfma_f32_16x16x32_bf16 v[24:27], v[182:185], v[208:211], v[24:27]
	v_mfma_f32_16x16x32_bf16 v[16:19], v[174:177], v[216:219], v[16:19]
	v_mfma_f32_16x16x32_bf16 v[8:11], v[182:185], v[216:219], v[8:11]
	v_mfma_f32_16x16x32_bf16 v[52:55], v[220:223], v[186:189], v[52:55]
	v_mfma_f32_16x16x32_bf16 v[44:47], v[228:231], v[186:189], v[44:47]
	v_mfma_f32_16x16x32_bf16 v[36:39], v[220:223], v[194:197], v[36:39]
	v_mfma_f32_16x16x32_bf16 v[28:31], v[228:231], v[194:197], v[28:31]
	v_mfma_f32_16x16x32_bf16 v[20:23], v[220:223], v[204:207], v[20:23]
	v_mfma_f32_16x16x32_bf16 v[12:15], v[228:231], v[204:207], v[12:15]
	v_mfma_f32_16x16x32_bf16 v[4:7], v[220:223], v[212:215], v[4:7]
	v_mfma_f32_16x16x32_bf16 v[0:3], v[228:231], v[212:215], v[0:3]
	v_mfma_f32_16x16x32_bf16 v[52:55], v[224:227], v[190:193], v[52:55]
	v_mfma_f32_16x16x32_bf16 v[44:47], v[232:235], v[190:193], v[44:47]
	v_mfma_f32_16x16x32_bf16 v[36:39], v[224:227], v[198:201], v[36:39]
	v_mfma_f32_16x16x32_bf16 v[28:31], v[232:235], v[198:201], v[28:31]
	v_mfma_f32_16x16x32_bf16 v[20:23], v[224:227], v[208:211], v[20:23]
	v_mfma_f32_16x16x32_bf16 v[12:15], v[232:235], v[208:211], v[12:15]
	v_mfma_f32_16x16x32_bf16 v[4:7], v[224:227], v[216:219], v[4:7]
	v_mfma_f32_16x16x32_bf16 v[0:3], v[232:235], v[216:219], v[0:3]
	s_setprio 0
	s_add_i32 s41, s41, 2
	s_add_u32 s30, s30, 0x100
	s_addc_u32 s31, s31, 0
	s_add_u32 s39, s39, 0x100
	s_addc_u32 s40, s40, 0
	s_cmp_gt_u32 s41, 13
	s_barrier
	s_cbranch_scc0 .LBB0_1243
	s_cmpk_lt_i32 s42, 0x80
	s_cbranch_scc0 .Lgu_sample
	v_lshlrev_b32_e32 v170, 2, v160
	v_add_u32_e32 v170, s92, v170
	ds_read_b32 v174, v170
	ds_read_b32 v176, v170 offset:64
	ds_read_b32 v156, v170 offset:128
	ds_read_b32 v154, v170 offset:192
	ds_read_b32 v152, v170 offset:512
	ds_read_b32 v150, v170 offset:576
	ds_read_b32 v148, v170 offset:640
	ds_read_b32 v146, v170 offset:704
	v_lshl_add_u32 v144, s42, 8, v160
	v_add_u32_e32 v145, 0x80, v144
	s_cmpk_lt_i32 s42, 0x80
	s_waitcnt lgkmcnt(0)
	v_pk_mul_f32 v[124:125], v[124:125], v[174:175] op_sel_hi:[1,0]
	v_mul_f32_e32 v172, 0xbfb8aa3b, v125
	v_exp_f32_e32 v173, v172
	v_mul_f32_e32 v169, 0xbfb8aa3b, v124
	v_exp_f32_e32 v169, v169
	v_pk_mul_f32 v[126:127], v[126:127], v[174:175] op_sel_hi:[1,0]
	v_pk_mul_f32 v[118:119], v[118:119], v[174:175] op_sel_hi:[1,0]
	v_add_f32_e32 v169, 1.0, v169
	v_rcp_f32_e32 v172, v169
	v_add_f32_e32 v169, 1.0, v173
	v_mul_f32_e32 v173, 0xbfb8aa3b, v126
	v_exp_f32_e32 v175, v173
	v_mul_f32_e32 v173, 0xbfb8aa3b, v127
	v_exp_f32_e32 v177, v173
	v_rcp_f32_e32 v173, v169
	v_add_f32_e32 v169, 1.0, v175
	v_rcp_f32_e32 v178, v169
	v_add_f32_e32 v169, 1.0, v177
	v_rcp_f32_e32 v179, v169
	v_pk_mul_f32 v[116:117], v[116:117], v[174:175] op_sel_hi:[1,0]
	v_pk_mul_f32 v[124:125], v[124:125], v[172:173]
	v_pk_mul_f32 v[120:121], v[120:121], v[174:175] op_sel_hi:[1,0]
	v_pk_mul_f32 v[116:117], v[116:117], v[124:125]
	v_pk_mul_f32 v[124:125], v[126:127], v[178:179]
	v_pk_mul_f32 v[122:123], v[122:123], v[174:175] op_sel_hi:[1,0]
	v_pk_mul_f32 v[118:119], v[118:119], v[124:125]
	v_mul_f32_e32 v124, 0xbfb8aa3b, v120
	v_mul_f32_e32 v125, 0xbfb8aa3b, v121
	v_exp_f32_e32 v124, v124
	v_exp_f32_e32 v125, v125
	v_mul_f32_e32 v126, 0xbfb8aa3b, v122
	v_mul_f32_e32 v127, 0xbfb8aa3b, v123
	v_exp_f32_e32 v126, v126
	v_exp_f32_e32 v127, v127
	v_add_f32_e32 v124, 1.0, v124
	v_add_f32_e32 v125, 1.0, v125
	v_rcp_f32_e32 v124, v124
	v_rcp_f32_e32 v125, v125
	v_add_f32_e32 v126, 1.0, v126
	v_add_f32_e32 v127, 1.0, v127
	v_rcp_f32_e32 v126, v126
	v_rcp_f32_e32 v127, v127
	v_pk_mul_f32 v[108:109], v[108:109], v[174:175] op_sel_hi:[1,0]
	v_pk_mul_f32 v[120:121], v[120:121], v[124:125]
	v_lshl_or_b32 v170, s28, 7, v161
	v_pk_mul_f32 v[110:111], v[110:111], v[174:175] op_sel_hi:[1,0]
	v_pk_mul_f32 v[108:109], v[108:109], v[120:121]
	v_pk_mul_f32 v[120:121], v[122:123], v[126:127]
	v_ashrrev_i32_e32 v171, 31, v170
	v_pk_mul_f32 v[110:111], v[110:111], v[120:121]
	v_cvt_pk_bf16_f32 v116, v116, v117
	v_cvt_pk_bf16_f32 v117, v118, v119
	v_cvt_pk_bf16_f32 v118, v108, v109
	v_mov_b64_e32 v[108:109], s[6:7]
	v_cvt_pk_bf16_f32 v119, v110, v111
	v_mad_i64_i32 v[120:121], s[28:29], v144, s68, v[108:109]
	v_lshlrev_b64 v[110:111], 1, v[170:171]
	v_lshl_add_u64 v[120:121], v[120:121], 0, v[110:111]
	v_pk_mul_f32 v[112:113], v[112:113], v[176:177] op_sel_hi:[1,0]
	global_store_dwordx4 v[120:121], v[116:119], off
	v_pk_mul_f32 v[114:115], v[114:115], v[176:177] op_sel_hi:[1,0]
	v_pk_mul_f32 v[100:101], v[100:101], v[176:177] op_sel_hi:[1,0]
	v_mul_f32_e32 v116, 0xbfb8aa3b, v112
	v_mul_f32_e32 v117, 0xbfb8aa3b, v113
	v_exp_f32_e32 v116, v116
	v_exp_f32_e32 v117, v117
	v_mul_f32_e32 v118, 0xbfb8aa3b, v114
	v_mul_f32_e32 v119, 0xbfb8aa3b, v115
	v_exp_f32_e32 v118, v118
	v_exp_f32_e32 v119, v119
	v_add_f32_e32 v116, 1.0, v116
	v_add_f32_e32 v117, 1.0, v117
	v_rcp_f32_e32 v116, v116
	v_rcp_f32_e32 v117, v117
	v_add_f32_e32 v118, 1.0, v118
	v_add_f32_e32 v119, 1.0, v119
	v_rcp_f32_e32 v118, v118
	v_rcp_f32_e32 v119, v119
	v_pk_mul_f32 v[112:113], v[112:113], v[116:117]
	v_pk_mul_f32 v[102:103], v[102:103], v[176:177] op_sel_hi:[1,0]
	v_pk_mul_f32 v[100:101], v[100:101], v[112:113]
	v_pk_mul_f32 v[112:113], v[114:115], v[118:119]
	v_pk_mul_f32 v[104:105], v[104:105], v[176:177] op_sel_hi:[1,0]
	v_pk_mul_f32 v[102:103], v[102:103], v[112:113]
	v_pk_mul_f32 v[106:107], v[106:107], v[176:177] op_sel_hi:[1,0]
	v_mul_f32_e32 v112, 0xbfb8aa3b, v104
	v_mul_f32_e32 v113, 0xbfb8aa3b, v105
	v_exp_f32_e32 v112, v112
	v_exp_f32_e32 v113, v113
	v_mul_f32_e32 v114, 0xbfb8aa3b, v106
	v_mul_f32_e32 v115, 0xbfb8aa3b, v107
	v_exp_f32_e32 v114, v114
	v_exp_f32_e32 v115, v115
	v_add_f32_e32 v112, 1.0, v112
	v_add_f32_e32 v113, 1.0, v113
	v_rcp_f32_e32 v112, v112
	v_rcp_f32_e32 v113, v113
	v_add_f32_e32 v114, 1.0, v114
	v_add_f32_e32 v115, 1.0, v115
	v_rcp_f32_e32 v114, v114
	v_rcp_f32_e32 v115, v115
	v_pk_mul_f32 v[92:93], v[92:93], v[176:177] op_sel_hi:[1,0]
	v_pk_mul_f32 v[104:105], v[104:105], v[112:113]
	v_pk_mul_f32 v[94:95], v[94:95], v[176:177] op_sel_hi:[1,0]
	v_pk_mul_f32 v[104:105], v[92:93], v[104:105]
	v_pk_mul_f32 v[92:93], v[106:107], v[114:115]
	v_or_b32_e32 v112, 16, v144
	v_pk_mul_f32 v[106:107], v[94:95], v[92:93]
	v_cvt_pk_bf16_f32 v92, v100, v101
	v_mad_i64_i32 v[100:101], s[28:29], v112, s68, v[108:109]
	v_cvt_pk_bf16_f32 v93, v102, v103
	v_cvt_pk_bf16_f32 v94, v104, v105
	v_cvt_pk_bf16_f32 v95, v106, v107
	v_lshl_add_u64 v[100:101], v[100:101], 0, v[110:111]
	global_store_dwordx4 v[100:101], v[92:95], off
	v_pk_mul_f32 v[86:87], v[86:87], v[156:157] op_sel_hi:[1,0]
	v_pk_mul_f32 v[88:89], v[88:89], v[156:157] op_sel_hi:[1,0]
	v_pk_mul_f32 v[92:93], v[98:99], v[156:157] op_sel_hi:[1,0]
	v_pk_mul_f32 v[94:95], v[96:97], v[156:157] op_sel_hi:[1,0]
	v_mul_f32_e32 v98, 0xbfb8aa3b, v92
	v_mul_f32_e32 v99, 0xbfb8aa3b, v93
	v_mul_f32_e32 v96, 0xbfb8aa3b, v94
	v_mul_f32_e32 v97, 0xbfb8aa3b, v95
	v_exp_f32_e32 v98, v98
	v_exp_f32_e32 v99, v99
	v_exp_f32_e32 v96, v96
	v_exp_f32_e32 v97, v97
	v_add_f32_e32 v98, 1.0, v98
	v_add_f32_e32 v99, 1.0, v99
	v_add_f32_e32 v96, 1.0, v96
	v_add_f32_e32 v97, 1.0, v97
	v_rcp_f32_e32 v98, v98
	v_rcp_f32_e32 v99, v99
	v_rcp_f32_e32 v96, v96
	v_rcp_f32_e32 v97, v97
	v_pk_mul_f32 v[84:85], v[84:85], v[156:157] op_sel_hi:[1,0]
	v_pk_mul_f32 v[92:93], v[92:93], v[98:99]
	v_pk_mul_f32 v[90:91], v[90:91], v[156:157] op_sel_hi:[1,0]
	v_pk_mul_f32 v[94:95], v[94:95], v[96:97]
	v_pk_mul_f32 v[86:87], v[86:87], v[92:93]
	v_mul_f32_e32 v92, 0xbfb8aa3b, v88
	v_mul_f32_e32 v93, 0xbfb8aa3b, v89
	v_pk_mul_f32 v[84:85], v[84:85], v[94:95]
	v_exp_f32_e32 v92, v92
	v_exp_f32_e32 v93, v93
	v_mul_f32_e32 v94, 0xbfb8aa3b, v90
	v_mul_f32_e32 v95, 0xbfb8aa3b, v91
	v_exp_f32_e32 v94, v94
	v_exp_f32_e32 v95, v95
	v_add_f32_e32 v92, 1.0, v92
	v_add_f32_e32 v93, 1.0, v93
	v_rcp_f32_e32 v92, v92
	v_rcp_f32_e32 v93, v93
	v_add_f32_e32 v94, 1.0, v94
	v_add_f32_e32 v95, 1.0, v95
	v_rcp_f32_e32 v94, v94
	v_rcp_f32_e32 v95, v95
	v_pk_mul_f32 v[76:77], v[76:77], v[156:157] op_sel_hi:[1,0]
	v_pk_mul_f32 v[88:89], v[88:89], v[92:93]
	v_pk_mul_f32 v[78:79], v[78:79], v[156:157] op_sel_hi:[1,0]
	v_pk_mul_f32 v[88:89], v[76:77], v[88:89]
	v_pk_mul_f32 v[76:77], v[90:91], v[94:95]
	v_or_b32_e32 v92, 32, v144
	v_pk_mul_f32 v[90:91], v[78:79], v[76:77]
	v_cvt_pk_bf16_f32 v76, v84, v85
	v_mad_i64_i32 v[84:85], s[28:29], v92, s68, v[108:109]
	v_cvt_pk_bf16_f32 v77, v86, v87
	v_cvt_pk_bf16_f32 v78, v88, v89
	v_cvt_pk_bf16_f32 v79, v90, v91
	v_lshl_add_u64 v[84:85], v[84:85], 0, v[110:111]
	global_store_dwordx4 v[84:85], v[76:79], off
	v_pk_mul_f32 v[70:71], v[70:71], v[154:155] op_sel_hi:[1,0]
	v_pk_mul_f32 v[72:73], v[72:73], v[154:155] op_sel_hi:[1,0]
	v_pk_mul_f32 v[76:77], v[82:83], v[154:155] op_sel_hi:[1,0]
	v_pk_mul_f32 v[78:79], v[80:81], v[154:155] op_sel_hi:[1,0]
	v_mul_f32_e32 v82, 0xbfb8aa3b, v76
	v_mul_f32_e32 v83, 0xbfb8aa3b, v77
	v_mul_f32_e32 v80, 0xbfb8aa3b, v78
	v_mul_f32_e32 v81, 0xbfb8aa3b, v79
	v_exp_f32_e32 v82, v82
	v_exp_f32_e32 v83, v83
	v_exp_f32_e32 v80, v80
	v_exp_f32_e32 v81, v81
	v_add_f32_e32 v82, 1.0, v82
	v_add_f32_e32 v83, 1.0, v83
	v_add_f32_e32 v80, 1.0, v80
	v_add_f32_e32 v81, 1.0, v81
	v_rcp_f32_e32 v82, v82
	v_rcp_f32_e32 v83, v83
	v_rcp_f32_e32 v80, v80
	v_rcp_f32_e32 v81, v81
	v_pk_mul_f32 v[68:69], v[68:69], v[154:155] op_sel_hi:[1,0]
	v_pk_mul_f32 v[76:77], v[76:77], v[82:83]
	v_pk_mul_f32 v[74:75], v[74:75], v[154:155] op_sel_hi:[1,0]
	v_pk_mul_f32 v[78:79], v[78:79], v[80:81]
	v_pk_mul_f32 v[70:71], v[70:71], v[76:77]
	v_mul_f32_e32 v76, 0xbfb8aa3b, v72
	v_mul_f32_e32 v77, 0xbfb8aa3b, v73
	v_pk_mul_f32 v[68:69], v[68:69], v[78:79]
	v_exp_f32_e32 v76, v76
	v_exp_f32_e32 v77, v77
	v_mul_f32_e32 v78, 0xbfb8aa3b, v74
	v_mul_f32_e32 v79, 0xbfb8aa3b, v75
	v_exp_f32_e32 v78, v78
	v_exp_f32_e32 v79, v79
	v_add_f32_e32 v76, 1.0, v76
	v_add_f32_e32 v77, 1.0, v77
	v_rcp_f32_e32 v76, v76
	v_rcp_f32_e32 v77, v77
	v_add_f32_e32 v78, 1.0, v78
	v_add_f32_e32 v79, 1.0, v79
	v_rcp_f32_e32 v78, v78
	v_rcp_f32_e32 v79, v79
	v_pk_mul_f32 v[64:65], v[64:65], v[154:155] op_sel_hi:[1,0]
	v_pk_mul_f32 v[72:73], v[72:73], v[76:77]
	v_pk_mul_f32 v[66:67], v[66:67], v[154:155] op_sel_hi:[1,0]
	v_pk_mul_f32 v[72:73], v[64:65], v[72:73]
	v_pk_mul_f32 v[64:65], v[74:75], v[78:79]
	v_or_b32_e32 v76, 48, v144
	v_pk_mul_f32 v[74:75], v[66:67], v[64:65]
	v_cvt_pk_bf16_f32 v64, v68, v69
	v_mad_i64_i32 v[68:69], s[28:29], v76, s68, v[108:109]
	v_cvt_pk_bf16_f32 v65, v70, v71
	v_cvt_pk_bf16_f32 v66, v72, v73
	v_cvt_pk_bf16_f32 v67, v74, v75
	v_lshl_add_u64 v[68:69], v[68:69], 0, v[110:111]
	v_pk_mul_f32 v[60:61], v[60:61], v[152:153] op_sel_hi:[1,0]
	global_store_dwordx4 v[68:69], v[64:67], off
	v_pk_mul_f32 v[62:63], v[62:63], v[152:153] op_sel_hi:[1,0]
	v_pk_mul_f32 v[52:53], v[52:53], v[152:153] op_sel_hi:[1,0]
	v_mul_f32_e32 v64, 0xbfb8aa3b, v60
	v_mul_f32_e32 v65, 0xbfb8aa3b, v61
	v_exp_f32_e32 v64, v64
	v_exp_f32_e32 v65, v65
	v_mul_f32_e32 v66, 0xbfb8aa3b, v62
	v_mul_f32_e32 v67, 0xbfb8aa3b, v63
	v_exp_f32_e32 v66, v66
	v_exp_f32_e32 v67, v67
	v_add_f32_e32 v64, 1.0, v64
	v_add_f32_e32 v65, 1.0, v65
	v_rcp_f32_e32 v64, v64
	v_rcp_f32_e32 v65, v65
	v_add_f32_e32 v66, 1.0, v66
	v_add_f32_e32 v67, 1.0, v67
	v_rcp_f32_e32 v66, v66
	v_rcp_f32_e32 v67, v67
	v_pk_mul_f32 v[60:61], v[60:61], v[64:65]
	v_pk_mul_f32 v[54:55], v[54:55], v[152:153] op_sel_hi:[1,0]
	v_pk_mul_f32 v[52:53], v[52:53], v[60:61]
	v_pk_mul_f32 v[60:61], v[62:63], v[66:67]
	v_pk_mul_f32 v[56:57], v[56:57], v[152:153] op_sel_hi:[1,0]
	v_pk_mul_f32 v[54:55], v[54:55], v[60:61]
	v_pk_mul_f32 v[58:59], v[58:59], v[152:153] op_sel_hi:[1,0]
	v_mul_f32_e32 v60, 0xbfb8aa3b, v56
	v_mul_f32_e32 v61, 0xbfb8aa3b, v57
	v_exp_f32_e32 v60, v60
	v_exp_f32_e32 v61, v61
	v_mul_f32_e32 v62, 0xbfb8aa3b, v58
	v_mul_f32_e32 v63, 0xbfb8aa3b, v59
	v_exp_f32_e32 v62, v62
	v_exp_f32_e32 v63, v63
	v_add_f32_e32 v60, 1.0, v60
	v_add_f32_e32 v61, 1.0, v61
	v_rcp_f32_e32 v60, v60
	v_rcp_f32_e32 v61, v61
	v_add_f32_e32 v62, 1.0, v62
	v_add_f32_e32 v63, 1.0, v63
	v_rcp_f32_e32 v62, v62
	v_rcp_f32_e32 v63, v63
	v_pk_mul_f32 v[44:45], v[44:45], v[152:153] op_sel_hi:[1,0]
	v_pk_mul_f32 v[56:57], v[56:57], v[60:61]
	v_pk_mul_f32 v[46:47], v[46:47], v[152:153] op_sel_hi:[1,0]
	v_pk_mul_f32 v[56:57], v[44:45], v[56:57]
	v_pk_mul_f32 v[44:45], v[58:59], v[62:63]
	v_pk_mul_f32 v[38:39], v[38:39], v[150:151] op_sel_hi:[1,0]
	v_pk_mul_f32 v[58:59], v[46:47], v[44:45]
	v_cvt_pk_bf16_f32 v44, v52, v53
	v_mad_i64_i32 v[52:53], s[28:29], v145, s68, v[108:109]
	v_cvt_pk_bf16_f32 v45, v54, v55
	v_cvt_pk_bf16_f32 v46, v56, v57
	v_cvt_pk_bf16_f32 v47, v58, v59
	v_lshl_add_u64 v[52:53], v[52:53], 0, v[110:111]
	global_store_dwordx4 v[52:53], v[44:47], off
	v_pk_mul_f32 v[40:41], v[40:41], v[150:151] op_sel_hi:[1,0]
	v_pk_mul_f32 v[36:37], v[36:37], v[150:151] op_sel_hi:[1,0]
	v_pk_mul_f32 v[44:45], v[50:51], v[150:151] op_sel_hi:[1,0]
	v_pk_mul_f32 v[46:47], v[48:49], v[150:151] op_sel_hi:[1,0]
	v_mul_f32_e32 v50, 0xbfb8aa3b, v44
	v_mul_f32_e32 v51, 0xbfb8aa3b, v45
	v_mul_f32_e32 v48, 0xbfb8aa3b, v46
	v_mul_f32_e32 v49, 0xbfb8aa3b, v47
	v_exp_f32_e32 v50, v50
	v_exp_f32_e32 v51, v51
	v_exp_f32_e32 v48, v48
	v_exp_f32_e32 v49, v49
	v_add_f32_e32 v50, 1.0, v50
	v_add_f32_e32 v51, 1.0, v51
	v_add_f32_e32 v48, 1.0, v48
	v_add_f32_e32 v49, 1.0, v49
	v_rcp_f32_e32 v50, v50
	v_rcp_f32_e32 v51, v51
	v_rcp_f32_e32 v48, v48
	v_rcp_f32_e32 v49, v49
	v_pk_mul_f32 v[42:43], v[42:43], v[150:151] op_sel_hi:[1,0]
	v_pk_mul_f32 v[44:45], v[44:45], v[50:51]
	v_pk_mul_f32 v[46:47], v[46:47], v[48:49]
	v_pk_mul_f32 v[38:39], v[38:39], v[44:45]
	v_mul_f32_e32 v44, 0xbfb8aa3b, v40
	v_mul_f32_e32 v45, 0xbfb8aa3b, v41
	v_pk_mul_f32 v[36:37], v[36:37], v[46:47]
	v_exp_f32_e32 v44, v44
	v_exp_f32_e32 v45, v45
	v_mul_f32_e32 v46, 0xbfb8aa3b, v42
	v_mul_f32_e32 v47, 0xbfb8aa3b, v43
	v_exp_f32_e32 v46, v46
	v_exp_f32_e32 v47, v47
	v_add_f32_e32 v44, 1.0, v44
	v_add_f32_e32 v45, 1.0, v45
	v_rcp_f32_e32 v44, v44
	v_rcp_f32_e32 v45, v45
	v_add_f32_e32 v46, 1.0, v46
	v_add_f32_e32 v47, 1.0, v47
	v_rcp_f32_e32 v46, v46
	v_rcp_f32_e32 v47, v47
	v_pk_mul_f32 v[28:29], v[28:29], v[150:151] op_sel_hi:[1,0]
	v_pk_mul_f32 v[40:41], v[40:41], v[44:45]
	v_pk_mul_f32 v[30:31], v[30:31], v[150:151] op_sel_hi:[1,0]
	v_pk_mul_f32 v[40:41], v[28:29], v[40:41]
	v_pk_mul_f32 v[28:29], v[42:43], v[46:47]
	v_add_u32_e32 v44, 0x90, v144
	v_pk_mul_f32 v[42:43], v[30:31], v[28:29]
	v_cvt_pk_bf16_f32 v28, v36, v37
	v_mad_i64_i32 v[36:37], s[28:29], v44, s68, v[108:109]
	v_cvt_pk_bf16_f32 v29, v38, v39
	v_cvt_pk_bf16_f32 v30, v40, v41
	v_cvt_pk_bf16_f32 v31, v42, v43
	v_lshl_add_u64 v[36:37], v[36:37], 0, v[110:111]
	global_store_dwordx4 v[36:37], v[28:31], off
	v_pk_mul_f32 v[22:23], v[22:23], v[148:149] op_sel_hi:[1,0]
	v_pk_mul_f32 v[24:25], v[24:25], v[148:149] op_sel_hi:[1,0]
	v_pk_mul_f32 v[28:29], v[34:35], v[148:149] op_sel_hi:[1,0]
	v_pk_mul_f32 v[30:31], v[32:33], v[148:149] op_sel_hi:[1,0]
	v_mul_f32_e32 v34, 0xbfb8aa3b, v28
	v_mul_f32_e32 v35, 0xbfb8aa3b, v29
	v_mul_f32_e32 v32, 0xbfb8aa3b, v30
	v_mul_f32_e32 v33, 0xbfb8aa3b, v31
	v_exp_f32_e32 v34, v34
	v_exp_f32_e32 v35, v35
	v_exp_f32_e32 v32, v32
	v_exp_f32_e32 v33, v33
	v_add_f32_e32 v34, 1.0, v34
	v_add_f32_e32 v35, 1.0, v35
	v_add_f32_e32 v32, 1.0, v32
	v_add_f32_e32 v33, 1.0, v33
	v_rcp_f32_e32 v34, v34
	v_rcp_f32_e32 v35, v35
	v_rcp_f32_e32 v32, v32
	v_rcp_f32_e32 v33, v33
	v_pk_mul_f32 v[20:21], v[20:21], v[148:149] op_sel_hi:[1,0]
	v_pk_mul_f32 v[28:29], v[28:29], v[34:35]
	v_pk_mul_f32 v[26:27], v[26:27], v[148:149] op_sel_hi:[1,0]
	v_pk_mul_f32 v[30:31], v[30:31], v[32:33]
	v_pk_mul_f32 v[22:23], v[22:23], v[28:29]
	v_mul_f32_e32 v28, 0xbfb8aa3b, v24
	v_mul_f32_e32 v29, 0xbfb8aa3b, v25
	v_pk_mul_f32 v[20:21], v[20:21], v[30:31]
	v_exp_f32_e32 v28, v28
	v_exp_f32_e32 v29, v29
	v_mul_f32_e32 v30, 0xbfb8aa3b, v26
	v_mul_f32_e32 v31, 0xbfb8aa3b, v27
	v_exp_f32_e32 v30, v30
	v_exp_f32_e32 v31, v31
	v_add_f32_e32 v28, 1.0, v28
	v_add_f32_e32 v29, 1.0, v29
	v_rcp_f32_e32 v28, v28
	v_rcp_f32_e32 v29, v29
	v_add_f32_e32 v30, 1.0, v30
	v_add_f32_e32 v31, 1.0, v31
	v_rcp_f32_e32 v30, v30
	v_rcp_f32_e32 v31, v31
	v_pk_mul_f32 v[12:13], v[12:13], v[148:149] op_sel_hi:[1,0]
	v_pk_mul_f32 v[24:25], v[24:25], v[28:29]
	v_pk_mul_f32 v[14:15], v[14:15], v[148:149] op_sel_hi:[1,0]
	v_pk_mul_f32 v[24:25], v[12:13], v[24:25]
	v_pk_mul_f32 v[12:13], v[26:27], v[30:31]
	v_add_u32_e32 v28, 0xa0, v144
	v_pk_mul_f32 v[26:27], v[14:15], v[12:13]
	v_cvt_pk_bf16_f32 v12, v20, v21
	v_mad_i64_i32 v[20:21], s[28:29], v28, s68, v[108:109]
	v_cvt_pk_bf16_f32 v13, v22, v23
	v_cvt_pk_bf16_f32 v14, v24, v25
	v_cvt_pk_bf16_f32 v15, v26, v27
	v_lshl_add_u64 v[20:21], v[20:21], 0, v[110:111]
	global_store_dwordx4 v[20:21], v[12:15], off
	v_pk_mul_f32 v[6:7], v[6:7], v[146:147] op_sel_hi:[1,0]
	v_pk_mul_f32 v[8:9], v[8:9], v[146:147] op_sel_hi:[1,0]
	v_pk_mul_f32 v[12:13], v[18:19], v[146:147] op_sel_hi:[1,0]
	v_pk_mul_f32 v[14:15], v[16:17], v[146:147] op_sel_hi:[1,0]
	v_mul_f32_e32 v18, 0xbfb8aa3b, v12
	v_mul_f32_e32 v19, 0xbfb8aa3b, v13
	v_mul_f32_e32 v16, 0xbfb8aa3b, v14
	v_mul_f32_e32 v17, 0xbfb8aa3b, v15
	v_exp_f32_e32 v18, v18
	v_exp_f32_e32 v19, v19
	v_exp_f32_e32 v16, v16
	v_exp_f32_e32 v17, v17
	v_add_f32_e32 v18, 1.0, v18
	v_add_f32_e32 v19, 1.0, v19
	v_add_f32_e32 v16, 1.0, v16
	v_add_f32_e32 v17, 1.0, v17
	v_rcp_f32_e32 v18, v18
	v_rcp_f32_e32 v19, v19
	v_rcp_f32_e32 v16, v16
	v_rcp_f32_e32 v17, v17
	v_pk_mul_f32 v[4:5], v[4:5], v[146:147] op_sel_hi:[1,0]
	v_pk_mul_f32 v[12:13], v[12:13], v[18:19]
	v_pk_mul_f32 v[10:11], v[10:11], v[146:147] op_sel_hi:[1,0]
	v_pk_mul_f32 v[14:15], v[14:15], v[16:17]
	v_pk_mul_f32 v[6:7], v[6:7], v[12:13]
	v_mul_f32_e32 v12, 0xbfb8aa3b, v8
	v_mul_f32_e32 v13, 0xbfb8aa3b, v9
	v_pk_mul_f32 v[4:5], v[4:5], v[14:15]
	v_exp_f32_e32 v12, v12
	v_exp_f32_e32 v13, v13
	v_mul_f32_e32 v14, 0xbfb8aa3b, v10
	v_mul_f32_e32 v15, 0xbfb8aa3b, v11
	v_exp_f32_e32 v14, v14
	v_exp_f32_e32 v15, v15
	v_add_f32_e32 v12, 1.0, v12
	v_add_f32_e32 v13, 1.0, v13
	v_rcp_f32_e32 v12, v12
	v_rcp_f32_e32 v13, v13
	v_add_f32_e32 v14, 1.0, v14
	v_add_f32_e32 v15, 1.0, v15
	v_rcp_f32_e32 v14, v14
	v_rcp_f32_e32 v15, v15
	v_pk_mul_f32 v[0:1], v[0:1], v[146:147] op_sel_hi:[1,0]
	v_pk_mul_f32 v[8:9], v[8:9], v[12:13]
	v_pk_mul_f32 v[2:3], v[2:3], v[146:147] op_sel_hi:[1,0]
	v_pk_mul_f32 v[8:9], v[0:1], v[8:9]
	v_pk_mul_f32 v[0:1], v[10:11], v[14:15]
	v_add_u32_e32 v12, 0xb0, v144
	v_pk_mul_f32 v[10:11], v[2:3], v[0:1]
	v_cvt_pk_bf16_f32 v0, v4, v5
	v_mad_i64_i32 v[4:5], s[28:29], v12, s68, v[108:109]
	v_cvt_pk_bf16_f32 v1, v6, v7
	v_cvt_pk_bf16_f32 v2, v8, v9
	v_cvt_pk_bf16_f32 v3, v10, v11
	v_lshl_add_u64 v[4:5], v[4:5], 0, v[110:111]
	global_store_dwordx4 v[4:5], v[0:3], off
	s_cbranch_scc1 .LBB0_1226
	s_waitcnt vmcnt(0)
	buffer_wbl2 sc1
	s_waitcnt vmcnt(0)
	s_waitcnt vmcnt(0)
	s_and_saveexec_b64 s[28:29], s[4:5]
	s_cbranch_execz .LBB0_1225
	s_mov_b64 s[30:31], exec
	v_mbcnt_lo_u32_b32 v0, s30, 0
	v_mbcnt_hi_u32_b32 v0, s31, v0
	v_cmp_eq_u32_e32 vcc, 0, v0
	s_and_b64 s[34:35], exec, vcc
	s_mov_b64 exec, s[34:35]
	s_cbranch_execz .LBB0_1225
	s_bcnt1_i32_b64 s11, s[30:31]
	v_mov_b32_e32 v0, s11
	global_atomic_add v129, v0, s[8:9]
	s_branch .LBB0_1225
.Lgu_sample:
	v_lshlrev_b32_e32 v170, 2, v160
	v_add_u32_e32 v170, s92, v170
	ds_read_b32 v174, v170
	ds_read_b32 v176, v170 offset:64
	ds_read_b32 v156, v170 offset:128
	ds_read_b32 v154, v170 offset:192
	ds_read_b32 v152, v170 offset:512
	ds_read_b32 v150, v170 offset:576
	ds_read_b32 v148, v170 offset:640
	ds_read_b32 v146, v170 offset:704
	v_lshl_add_u32 v144, s42, 8, v160
	v_add_u32_e32 v145, 0x80, v144
	s_cmpk_lt_i32 s42, 0x80
	s_waitcnt lgkmcnt(0)
	v_pk_mul_f32 v[124:125], v[124:125], v[174:175] op_sel_hi:[1,0]
	v_mul_f32_e32 v172, 0xbfb8aa3b, v125
	v_exp_f32_e32 v173, v172
	v_mul_f32_e32 v169, 0xbfb8aa3b, v124
	v_exp_f32_e32 v169, v169
	v_pk_mul_f32 v[126:127], v[126:127], v[174:175] op_sel_hi:[1,0]
	v_pk_mul_f32 v[118:119], v[118:119], v[174:175] op_sel_hi:[1,0]
	v_add_f32_e32 v169, 1.0, v169
	v_rcp_f32_e32 v172, v169
	v_add_f32_e32 v169, 1.0, v173
	v_mul_f32_e32 v173, 0xbfb8aa3b, v126
	v_exp_f32_e32 v175, v173
	v_mul_f32_e32 v173, 0xbfb8aa3b, v127
	v_exp_f32_e32 v177, v173
	v_rcp_f32_e32 v173, v169
	v_add_f32_e32 v169, 1.0, v175
	v_rcp_f32_e32 v178, v169
	v_add_f32_e32 v169, 1.0, v177
	v_rcp_f32_e32 v179, v169
	v_pk_mul_f32 v[116:117], v[116:117], v[174:175] op_sel_hi:[1,0]
	v_pk_mul_f32 v[124:125], v[124:125], v[172:173]
	v_pk_mul_f32 v[120:121], v[120:121], v[174:175] op_sel_hi:[1,0]
	v_pk_mul_f32 v[116:117], v[116:117], v[124:125]
	v_pk_mul_f32 v[124:125], v[126:127], v[178:179]
	v_pk_mul_f32 v[122:123], v[122:123], v[174:175] op_sel_hi:[1,0]
	v_pk_mul_f32 v[118:119], v[118:119], v[124:125]
	v_mul_f32_e32 v124, 0xbfb8aa3b, v120
	v_mul_f32_e32 v125, 0xbfb8aa3b, v121
	v_exp_f32_e32 v124, v124
	v_exp_f32_e32 v125, v125
	v_mul_f32_e32 v126, 0xbfb8aa3b, v122
	v_mul_f32_e32 v127, 0xbfb8aa3b, v123
	v_exp_f32_e32 v126, v126
	v_exp_f32_e32 v127, v127
	v_add_f32_e32 v124, 1.0, v124
	v_add_f32_e32 v125, 1.0, v125
	v_rcp_f32_e32 v124, v124
	v_rcp_f32_e32 v125, v125
	v_add_f32_e32 v126, 1.0, v126
	v_add_f32_e32 v127, 1.0, v127
	v_rcp_f32_e32 v126, v126
	v_rcp_f32_e32 v127, v127
	v_pk_mul_f32 v[108:109], v[108:109], v[174:175] op_sel_hi:[1,0]
	v_pk_mul_f32 v[120:121], v[120:121], v[124:125]
	v_lshl_or_b32 v170, s28, 7, v161
	v_pk_mul_f32 v[110:111], v[110:111], v[174:175] op_sel_hi:[1,0]
	v_pk_mul_f32 v[108:109], v[108:109], v[120:121]
	v_pk_mul_f32 v[120:121], v[122:123], v[126:127]
	v_ashrrev_i32_e32 v171, 31, v170
	v_pk_mul_f32 v[110:111], v[110:111], v[120:121]
	v_cvt_pk_bf16_f32 v116, v116, v117
	v_cvt_pk_bf16_f32 v117, v118, v119
	v_cvt_pk_bf16_f32 v118, v108, v109
	v_mov_b64_e32 v[108:109], s[6:7]
	v_cvt_pk_bf16_f32 v119, v110, v111
	v_mad_i64_i32 v[120:121], s[28:29], v144, s68, v[108:109]
	v_lshlrev_b64 v[110:111], 1, v[170:171]
	v_lshl_add_u64 v[120:121], v[120:121], 0, v[110:111]
	v_pk_mul_f32 v[112:113], v[112:113], v[176:177] op_sel_hi:[1,0]
	global_store_dwordx4 v[120:121], v[116:119], off sc1
	v_pk_mul_f32 v[114:115], v[114:115], v[176:177] op_sel_hi:[1,0]
	v_pk_mul_f32 v[100:101], v[100:101], v[176:177] op_sel_hi:[1,0]
	v_mul_f32_e32 v116, 0xbfb8aa3b, v112
	v_mul_f32_e32 v117, 0xbfb8aa3b, v113
	v_exp_f32_e32 v116, v116
	v_exp_f32_e32 v117, v117
	v_mul_f32_e32 v118, 0xbfb8aa3b, v114
	v_mul_f32_e32 v119, 0xbfb8aa3b, v115
	v_exp_f32_e32 v118, v118
	v_exp_f32_e32 v119, v119
	v_add_f32_e32 v116, 1.0, v116
	v_add_f32_e32 v117, 1.0, v117
	v_rcp_f32_e32 v116, v116
	v_rcp_f32_e32 v117, v117
	v_add_f32_e32 v118, 1.0, v118
	v_add_f32_e32 v119, 1.0, v119
	v_rcp_f32_e32 v118, v118
	v_rcp_f32_e32 v119, v119
	v_pk_mul_f32 v[112:113], v[112:113], v[116:117]
	v_pk_mul_f32 v[102:103], v[102:103], v[176:177] op_sel_hi:[1,0]
	v_pk_mul_f32 v[100:101], v[100:101], v[112:113]
	v_pk_mul_f32 v[112:113], v[114:115], v[118:119]
	v_pk_mul_f32 v[104:105], v[104:105], v[176:177] op_sel_hi:[1,0]
	v_pk_mul_f32 v[102:103], v[102:103], v[112:113]
	v_pk_mul_f32 v[106:107], v[106:107], v[176:177] op_sel_hi:[1,0]
	v_mul_f32_e32 v112, 0xbfb8aa3b, v104
	v_mul_f32_e32 v113, 0xbfb8aa3b, v105
	v_exp_f32_e32 v112, v112
	v_exp_f32_e32 v113, v113
	v_mul_f32_e32 v114, 0xbfb8aa3b, v106
	v_mul_f32_e32 v115, 0xbfb8aa3b, v107
	v_exp_f32_e32 v114, v114
	v_exp_f32_e32 v115, v115
	v_add_f32_e32 v112, 1.0, v112
	v_add_f32_e32 v113, 1.0, v113
	v_rcp_f32_e32 v112, v112
	v_rcp_f32_e32 v113, v113
	v_add_f32_e32 v114, 1.0, v114
	v_add_f32_e32 v115, 1.0, v115
	v_rcp_f32_e32 v114, v114
	v_rcp_f32_e32 v115, v115
	v_pk_mul_f32 v[92:93], v[92:93], v[176:177] op_sel_hi:[1,0]
	v_pk_mul_f32 v[104:105], v[104:105], v[112:113]
	v_pk_mul_f32 v[94:95], v[94:95], v[176:177] op_sel_hi:[1,0]
	v_pk_mul_f32 v[104:105], v[92:93], v[104:105]
	v_pk_mul_f32 v[92:93], v[106:107], v[114:115]
	v_or_b32_e32 v112, 16, v144
	v_pk_mul_f32 v[106:107], v[94:95], v[92:93]
	v_cvt_pk_bf16_f32 v92, v100, v101
	v_mad_i64_i32 v[100:101], s[28:29], v112, s68, v[108:109]
	v_cvt_pk_bf16_f32 v93, v102, v103
	v_cvt_pk_bf16_f32 v94, v104, v105
	v_cvt_pk_bf16_f32 v95, v106, v107
	v_lshl_add_u64 v[100:101], v[100:101], 0, v[110:111]
	global_store_dwordx4 v[100:101], v[92:95], off sc1
	v_pk_mul_f32 v[86:87], v[86:87], v[156:157] op_sel_hi:[1,0]
	v_pk_mul_f32 v[88:89], v[88:89], v[156:157] op_sel_hi:[1,0]
	v_pk_mul_f32 v[92:93], v[98:99], v[156:157] op_sel_hi:[1,0]
	v_pk_mul_f32 v[94:95], v[96:97], v[156:157] op_sel_hi:[1,0]
	v_mul_f32_e32 v98, 0xbfb8aa3b, v92
	v_mul_f32_e32 v99, 0xbfb8aa3b, v93
	v_mul_f32_e32 v96, 0xbfb8aa3b, v94
	v_mul_f32_e32 v97, 0xbfb8aa3b, v95
	v_exp_f32_e32 v98, v98
	v_exp_f32_e32 v99, v99
	v_exp_f32_e32 v96, v96
	v_exp_f32_e32 v97, v97
	v_add_f32_e32 v98, 1.0, v98
	v_add_f32_e32 v99, 1.0, v99
	v_add_f32_e32 v96, 1.0, v96
	v_add_f32_e32 v97, 1.0, v97
	v_rcp_f32_e32 v98, v98
	v_rcp_f32_e32 v99, v99
	v_rcp_f32_e32 v96, v96
	v_rcp_f32_e32 v97, v97
	v_pk_mul_f32 v[84:85], v[84:85], v[156:157] op_sel_hi:[1,0]
	v_pk_mul_f32 v[92:93], v[92:93], v[98:99]
	v_pk_mul_f32 v[90:91], v[90:91], v[156:157] op_sel_hi:[1,0]
	v_pk_mul_f32 v[94:95], v[94:95], v[96:97]
	v_pk_mul_f32 v[86:87], v[86:87], v[92:93]
	v_mul_f32_e32 v92, 0xbfb8aa3b, v88
	v_mul_f32_e32 v93, 0xbfb8aa3b, v89
	v_pk_mul_f32 v[84:85], v[84:85], v[94:95]
	v_exp_f32_e32 v92, v92
	v_exp_f32_e32 v93, v93
	v_mul_f32_e32 v94, 0xbfb8aa3b, v90
	v_mul_f32_e32 v95, 0xbfb8aa3b, v91
	v_exp_f32_e32 v94, v94
	v_exp_f32_e32 v95, v95
	v_add_f32_e32 v92, 1.0, v92
	v_add_f32_e32 v93, 1.0, v93
	v_rcp_f32_e32 v92, v92
	v_rcp_f32_e32 v93, v93
	v_add_f32_e32 v94, 1.0, v94
	v_add_f32_e32 v95, 1.0, v95
	v_rcp_f32_e32 v94, v94
	v_rcp_f32_e32 v95, v95
	v_pk_mul_f32 v[76:77], v[76:77], v[156:157] op_sel_hi:[1,0]
	v_pk_mul_f32 v[88:89], v[88:89], v[92:93]
	v_pk_mul_f32 v[78:79], v[78:79], v[156:157] op_sel_hi:[1,0]
	v_pk_mul_f32 v[88:89], v[76:77], v[88:89]
	v_pk_mul_f32 v[76:77], v[90:91], v[94:95]
	v_or_b32_e32 v92, 32, v144
	v_pk_mul_f32 v[90:91], v[78:79], v[76:77]
	v_cvt_pk_bf16_f32 v76, v84, v85
	v_mad_i64_i32 v[84:85], s[28:29], v92, s68, v[108:109]
	v_cvt_pk_bf16_f32 v77, v86, v87
	v_cvt_pk_bf16_f32 v78, v88, v89
	v_cvt_pk_bf16_f32 v79, v90, v91
	v_lshl_add_u64 v[84:85], v[84:85], 0, v[110:111]
	global_store_dwordx4 v[84:85], v[76:79], off sc1
	v_pk_mul_f32 v[70:71], v[70:71], v[154:155] op_sel_hi:[1,0]
	v_pk_mul_f32 v[72:73], v[72:73], v[154:155] op_sel_hi:[1,0]
	v_pk_mul_f32 v[76:77], v[82:83], v[154:155] op_sel_hi:[1,0]
	v_pk_mul_f32 v[78:79], v[80:81], v[154:155] op_sel_hi:[1,0]
	v_mul_f32_e32 v82, 0xbfb8aa3b, v76
	v_mul_f32_e32 v83, 0xbfb8aa3b, v77
	v_mul_f32_e32 v80, 0xbfb8aa3b, v78
	v_mul_f32_e32 v81, 0xbfb8aa3b, v79
	v_exp_f32_e32 v82, v82
	v_exp_f32_e32 v83, v83
	v_exp_f32_e32 v80, v80
	v_exp_f32_e32 v81, v81
	v_add_f32_e32 v82, 1.0, v82
	v_add_f32_e32 v83, 1.0, v83
	v_add_f32_e32 v80, 1.0, v80
	v_add_f32_e32 v81, 1.0, v81
	v_rcp_f32_e32 v82, v82
	v_rcp_f32_e32 v83, v83
	v_rcp_f32_e32 v80, v80
	v_rcp_f32_e32 v81, v81
	v_pk_mul_f32 v[68:69], v[68:69], v[154:155] op_sel_hi:[1,0]
	v_pk_mul_f32 v[76:77], v[76:77], v[82:83]
	v_pk_mul_f32 v[74:75], v[74:75], v[154:155] op_sel_hi:[1,0]
	v_pk_mul_f32 v[78:79], v[78:79], v[80:81]
	v_pk_mul_f32 v[70:71], v[70:71], v[76:77]
	v_mul_f32_e32 v76, 0xbfb8aa3b, v72
	v_mul_f32_e32 v77, 0xbfb8aa3b, v73
	v_pk_mul_f32 v[68:69], v[68:69], v[78:79]
	v_exp_f32_e32 v76, v76
	v_exp_f32_e32 v77, v77
	v_mul_f32_e32 v78, 0xbfb8aa3b, v74
	v_mul_f32_e32 v79, 0xbfb8aa3b, v75
	v_exp_f32_e32 v78, v78
	v_exp_f32_e32 v79, v79
	v_add_f32_e32 v76, 1.0, v76
	v_add_f32_e32 v77, 1.0, v77
	v_rcp_f32_e32 v76, v76
	v_rcp_f32_e32 v77, v77
	v_add_f32_e32 v78, 1.0, v78
	v_add_f32_e32 v79, 1.0, v79
	v_rcp_f32_e32 v78, v78
	v_rcp_f32_e32 v79, v79
	v_pk_mul_f32 v[64:65], v[64:65], v[154:155] op_sel_hi:[1,0]
	v_pk_mul_f32 v[72:73], v[72:73], v[76:77]
	v_pk_mul_f32 v[66:67], v[66:67], v[154:155] op_sel_hi:[1,0]
	v_pk_mul_f32 v[72:73], v[64:65], v[72:73]
	v_pk_mul_f32 v[64:65], v[74:75], v[78:79]
	v_or_b32_e32 v76, 48, v144
	v_pk_mul_f32 v[74:75], v[66:67], v[64:65]
	v_cvt_pk_bf16_f32 v64, v68, v69
	v_mad_i64_i32 v[68:69], s[28:29], v76, s68, v[108:109]
	v_cvt_pk_bf16_f32 v65, v70, v71
	v_cvt_pk_bf16_f32 v66, v72, v73
	v_cvt_pk_bf16_f32 v67, v74, v75
	v_lshl_add_u64 v[68:69], v[68:69], 0, v[110:111]
	v_pk_mul_f32 v[60:61], v[60:61], v[152:153] op_sel_hi:[1,0]
	global_store_dwordx4 v[68:69], v[64:67], off sc1
	v_pk_mul_f32 v[62:63], v[62:63], v[152:153] op_sel_hi:[1,0]
	v_pk_mul_f32 v[52:53], v[52:53], v[152:153] op_sel_hi:[1,0]
	v_mul_f32_e32 v64, 0xbfb8aa3b, v60
	v_mul_f32_e32 v65, 0xbfb8aa3b, v61
	v_exp_f32_e32 v64, v64
	v_exp_f32_e32 v65, v65
	v_mul_f32_e32 v66, 0xbfb8aa3b, v62
	v_mul_f32_e32 v67, 0xbfb8aa3b, v63
	v_exp_f32_e32 v66, v66
	v_exp_f32_e32 v67, v67
	v_add_f32_e32 v64, 1.0, v64
	v_add_f32_e32 v65, 1.0, v65
	v_rcp_f32_e32 v64, v64
	v_rcp_f32_e32 v65, v65
	v_add_f32_e32 v66, 1.0, v66
	v_add_f32_e32 v67, 1.0, v67
	v_rcp_f32_e32 v66, v66
	v_rcp_f32_e32 v67, v67
	v_pk_mul_f32 v[60:61], v[60:61], v[64:65]
	v_pk_mul_f32 v[54:55], v[54:55], v[152:153] op_sel_hi:[1,0]
	v_pk_mul_f32 v[52:53], v[52:53], v[60:61]
	v_pk_mul_f32 v[60:61], v[62:63], v[66:67]
	v_pk_mul_f32 v[56:57], v[56:57], v[152:153] op_sel_hi:[1,0]
	v_pk_mul_f32 v[54:55], v[54:55], v[60:61]
	v_pk_mul_f32 v[58:59], v[58:59], v[152:153] op_sel_hi:[1,0]
	v_mul_f32_e32 v60, 0xbfb8aa3b, v56
	v_mul_f32_e32 v61, 0xbfb8aa3b, v57
	v_exp_f32_e32 v60, v60
	v_exp_f32_e32 v61, v61
	v_mul_f32_e32 v62, 0xbfb8aa3b, v58
	v_mul_f32_e32 v63, 0xbfb8aa3b, v59
	v_exp_f32_e32 v62, v62
	v_exp_f32_e32 v63, v63
	v_add_f32_e32 v60, 1.0, v60
	v_add_f32_e32 v61, 1.0, v61
	v_rcp_f32_e32 v60, v60
	v_rcp_f32_e32 v61, v61
	v_add_f32_e32 v62, 1.0, v62
	v_add_f32_e32 v63, 1.0, v63
	v_rcp_f32_e32 v62, v62
	v_rcp_f32_e32 v63, v63
	v_pk_mul_f32 v[44:45], v[44:45], v[152:153] op_sel_hi:[1,0]
	v_pk_mul_f32 v[56:57], v[56:57], v[60:61]
	v_pk_mul_f32 v[46:47], v[46:47], v[152:153] op_sel_hi:[1,0]
	v_pk_mul_f32 v[56:57], v[44:45], v[56:57]
	v_pk_mul_f32 v[44:45], v[58:59], v[62:63]
	v_pk_mul_f32 v[38:39], v[38:39], v[150:151] op_sel_hi:[1,0]
	v_pk_mul_f32 v[58:59], v[46:47], v[44:45]
	v_cvt_pk_bf16_f32 v44, v52, v53
	v_mad_i64_i32 v[52:53], s[28:29], v145, s68, v[108:109]
	v_cvt_pk_bf16_f32 v45, v54, v55
	v_cvt_pk_bf16_f32 v46, v56, v57
	v_cvt_pk_bf16_f32 v47, v58, v59
	v_lshl_add_u64 v[52:53], v[52:53], 0, v[110:111]
	global_store_dwordx4 v[52:53], v[44:47], off sc1
	v_pk_mul_f32 v[40:41], v[40:41], v[150:151] op_sel_hi:[1,0]
	v_pk_mul_f32 v[36:37], v[36:37], v[150:151] op_sel_hi:[1,0]
	v_pk_mul_f32 v[44:45], v[50:51], v[150:151] op_sel_hi:[1,0]
	v_pk_mul_f32 v[46:47], v[48:49], v[150:151] op_sel_hi:[1,0]
	v_mul_f32_e32 v50, 0xbfb8aa3b, v44
	v_mul_f32_e32 v51, 0xbfb8aa3b, v45
	v_mul_f32_e32 v48, 0xbfb8aa3b, v46
	v_mul_f32_e32 v49, 0xbfb8aa3b, v47
	v_exp_f32_e32 v50, v50
	v_exp_f32_e32 v51, v51
	v_exp_f32_e32 v48, v48
	v_exp_f32_e32 v49, v49
	v_add_f32_e32 v50, 1.0, v50
	v_add_f32_e32 v51, 1.0, v51
	v_add_f32_e32 v48, 1.0, v48
	v_add_f32_e32 v49, 1.0, v49
	v_rcp_f32_e32 v50, v50
	v_rcp_f32_e32 v51, v51
	v_rcp_f32_e32 v48, v48
	v_rcp_f32_e32 v49, v49
	v_pk_mul_f32 v[42:43], v[42:43], v[150:151] op_sel_hi:[1,0]
	v_pk_mul_f32 v[44:45], v[44:45], v[50:51]
	v_pk_mul_f32 v[46:47], v[46:47], v[48:49]
	v_pk_mul_f32 v[38:39], v[38:39], v[44:45]
	v_mul_f32_e32 v44, 0xbfb8aa3b, v40
	v_mul_f32_e32 v45, 0xbfb8aa3b, v41
	v_pk_mul_f32 v[36:37], v[36:37], v[46:47]
	v_exp_f32_e32 v44, v44
	v_exp_f32_e32 v45, v45
	v_mul_f32_e32 v46, 0xbfb8aa3b, v42
	v_mul_f32_e32 v47, 0xbfb8aa3b, v43
	v_exp_f32_e32 v46, v46
	v_exp_f32_e32 v47, v47
	v_add_f32_e32 v44, 1.0, v44
	v_add_f32_e32 v45, 1.0, v45
	v_rcp_f32_e32 v44, v44
	v_rcp_f32_e32 v45, v45
	v_add_f32_e32 v46, 1.0, v46
	v_add_f32_e32 v47, 1.0, v47
	v_rcp_f32_e32 v46, v46
	v_rcp_f32_e32 v47, v47
	v_pk_mul_f32 v[28:29], v[28:29], v[150:151] op_sel_hi:[1,0]
	v_pk_mul_f32 v[40:41], v[40:41], v[44:45]
	v_pk_mul_f32 v[30:31], v[30:31], v[150:151] op_sel_hi:[1,0]
	v_pk_mul_f32 v[40:41], v[28:29], v[40:41]
	v_pk_mul_f32 v[28:29], v[42:43], v[46:47]
	v_add_u32_e32 v44, 0x90, v144
	v_pk_mul_f32 v[42:43], v[30:31], v[28:29]
	v_cvt_pk_bf16_f32 v28, v36, v37
	v_mad_i64_i32 v[36:37], s[28:29], v44, s68, v[108:109]
	v_cvt_pk_bf16_f32 v29, v38, v39
	v_cvt_pk_bf16_f32 v30, v40, v41
	v_cvt_pk_bf16_f32 v31, v42, v43
	v_lshl_add_u64 v[36:37], v[36:37], 0, v[110:111]
	global_store_dwordx4 v[36:37], v[28:31], off sc1
	v_pk_mul_f32 v[22:23], v[22:23], v[148:149] op_sel_hi:[1,0]
	v_pk_mul_f32 v[24:25], v[24:25], v[148:149] op_sel_hi:[1,0]
	v_pk_mul_f32 v[28:29], v[34:35], v[148:149] op_sel_hi:[1,0]
	v_pk_mul_f32 v[30:31], v[32:33], v[148:149] op_sel_hi:[1,0]
	v_mul_f32_e32 v34, 0xbfb8aa3b, v28
	v_mul_f32_e32 v35, 0xbfb8aa3b, v29
	v_mul_f32_e32 v32, 0xbfb8aa3b, v30
	v_mul_f32_e32 v33, 0xbfb8aa3b, v31
	v_exp_f32_e32 v34, v34
	v_exp_f32_e32 v35, v35
	v_exp_f32_e32 v32, v32
	v_exp_f32_e32 v33, v33
	v_add_f32_e32 v34, 1.0, v34
	v_add_f32_e32 v35, 1.0, v35
	v_add_f32_e32 v32, 1.0, v32
	v_add_f32_e32 v33, 1.0, v33
	v_rcp_f32_e32 v34, v34
	v_rcp_f32_e32 v35, v35
	v_rcp_f32_e32 v32, v32
	v_rcp_f32_e32 v33, v33
	v_pk_mul_f32 v[20:21], v[20:21], v[148:149] op_sel_hi:[1,0]
	v_pk_mul_f32 v[28:29], v[28:29], v[34:35]
	v_pk_mul_f32 v[26:27], v[26:27], v[148:149] op_sel_hi:[1,0]
	v_pk_mul_f32 v[30:31], v[30:31], v[32:33]
	v_pk_mul_f32 v[22:23], v[22:23], v[28:29]
	v_mul_f32_e32 v28, 0xbfb8aa3b, v24
	v_mul_f32_e32 v29, 0xbfb8aa3b, v25
	v_pk_mul_f32 v[20:21], v[20:21], v[30:31]
	v_exp_f32_e32 v28, v28
	v_exp_f32_e32 v29, v29
	v_mul_f32_e32 v30, 0xbfb8aa3b, v26
	v_mul_f32_e32 v31, 0xbfb8aa3b, v27
	v_exp_f32_e32 v30, v30
	v_exp_f32_e32 v31, v31
	v_add_f32_e32 v28, 1.0, v28
	v_add_f32_e32 v29, 1.0, v29
	v_rcp_f32_e32 v28, v28
	v_rcp_f32_e32 v29, v29
	v_add_f32_e32 v30, 1.0, v30
	v_add_f32_e32 v31, 1.0, v31
	v_rcp_f32_e32 v30, v30
	v_rcp_f32_e32 v31, v31
	v_pk_mul_f32 v[12:13], v[12:13], v[148:149] op_sel_hi:[1,0]
	v_pk_mul_f32 v[24:25], v[24:25], v[28:29]
	v_pk_mul_f32 v[14:15], v[14:15], v[148:149] op_sel_hi:[1,0]
	v_pk_mul_f32 v[24:25], v[12:13], v[24:25]
	v_pk_mul_f32 v[12:13], v[26:27], v[30:31]
	v_add_u32_e32 v28, 0xa0, v144
	v_pk_mul_f32 v[26:27], v[14:15], v[12:13]
	v_cvt_pk_bf16_f32 v12, v20, v21
	v_mad_i64_i32 v[20:21], s[28:29], v28, s68, v[108:109]
	v_cvt_pk_bf16_f32 v13, v22, v23
	v_cvt_pk_bf16_f32 v14, v24, v25
	v_cvt_pk_bf16_f32 v15, v26, v27
	v_lshl_add_u64 v[20:21], v[20:21], 0, v[110:111]
	global_store_dwordx4 v[20:21], v[12:15], off sc1
	v_pk_mul_f32 v[6:7], v[6:7], v[146:147] op_sel_hi:[1,0]
	v_pk_mul_f32 v[8:9], v[8:9], v[146:147] op_sel_hi:[1,0]
	v_pk_mul_f32 v[12:13], v[18:19], v[146:147] op_sel_hi:[1,0]
	v_pk_mul_f32 v[14:15], v[16:17], v[146:147] op_sel_hi:[1,0]
	v_mul_f32_e32 v18, 0xbfb8aa3b, v12
	v_mul_f32_e32 v19, 0xbfb8aa3b, v13
	v_mul_f32_e32 v16, 0xbfb8aa3b, v14
	v_mul_f32_e32 v17, 0xbfb8aa3b, v15
	v_exp_f32_e32 v18, v18
	v_exp_f32_e32 v19, v19
	v_exp_f32_e32 v16, v16
	v_exp_f32_e32 v17, v17
	v_add_f32_e32 v18, 1.0, v18
	v_add_f32_e32 v19, 1.0, v19
	v_add_f32_e32 v16, 1.0, v16
	v_add_f32_e32 v17, 1.0, v17
	v_rcp_f32_e32 v18, v18
	v_rcp_f32_e32 v19, v19
	v_rcp_f32_e32 v16, v16
	v_rcp_f32_e32 v17, v17
	v_pk_mul_f32 v[4:5], v[4:5], v[146:147] op_sel_hi:[1,0]
	v_pk_mul_f32 v[12:13], v[12:13], v[18:19]
	v_pk_mul_f32 v[10:11], v[10:11], v[146:147] op_sel_hi:[1,0]
	v_pk_mul_f32 v[14:15], v[14:15], v[16:17]
	v_pk_mul_f32 v[6:7], v[6:7], v[12:13]
	v_mul_f32_e32 v12, 0xbfb8aa3b, v8
	v_mul_f32_e32 v13, 0xbfb8aa3b, v9
	v_pk_mul_f32 v[4:5], v[4:5], v[14:15]
	v_exp_f32_e32 v12, v12
	v_exp_f32_e32 v13, v13
	v_mul_f32_e32 v14, 0xbfb8aa3b, v10
	v_mul_f32_e32 v15, 0xbfb8aa3b, v11
	v_exp_f32_e32 v14, v14
	v_exp_f32_e32 v15, v15
	v_add_f32_e32 v12, 1.0, v12
	v_add_f32_e32 v13, 1.0, v13
	v_rcp_f32_e32 v12, v12
	v_rcp_f32_e32 v13, v13
	v_add_f32_e32 v14, 1.0, v14
	v_add_f32_e32 v15, 1.0, v15
	v_rcp_f32_e32 v14, v14
	v_rcp_f32_e32 v15, v15
	v_pk_mul_f32 v[0:1], v[0:1], v[146:147] op_sel_hi:[1,0]
	v_pk_mul_f32 v[8:9], v[8:9], v[12:13]
	v_pk_mul_f32 v[2:3], v[2:3], v[146:147] op_sel_hi:[1,0]
	v_pk_mul_f32 v[8:9], v[0:1], v[8:9]
	v_pk_mul_f32 v[0:1], v[10:11], v[14:15]
	v_add_u32_e32 v12, 0xb0, v144
	v_pk_mul_f32 v[10:11], v[2:3], v[0:1]
	v_cvt_pk_bf16_f32 v0, v4, v5
	v_mad_i64_i32 v[4:5], s[28:29], v12, s68, v[108:109]
	v_cvt_pk_bf16_f32 v1, v6, v7
	v_cvt_pk_bf16_f32 v2, v8, v9
	v_cvt_pk_bf16_f32 v3, v10, v11
	v_lshl_add_u64 v[4:5], v[4:5], 0, v[110:111]
	global_store_dwordx4 v[4:5], v[0:3], off sc1
	s_cbranch_scc1 .LBB0_1226
	s_waitcnt vmcnt(0)
	s_waitcnt vmcnt(0)
	s_waitcnt vmcnt(0)
	s_and_saveexec_b64 s[28:29], s[4:5]
	s_cbranch_execz .LBB0_1225
	s_mov_b64 s[30:31], exec
	v_mbcnt_lo_u32_b32 v0, s30, 0
	v_mbcnt_hi_u32_b32 v0, s31, v0
	v_cmp_eq_u32_e32 vcc, 0, v0
	s_and_b64 s[34:35], exec, vcc
	s_mov_b64 exec, s[34:35]
	s_cbranch_execz .LBB0_1225
	s_bcnt1_i32_b64 s11, s[30:31]
	v_mov_b32_e32 v0, s11
	global_atomic_add v129, v0, s[8:9]
	s_branch .LBB0_1225
